# v5: + p1_kern load batching, Z zero-half stores dropped, grid!=256 fallbacks
# speedup vs baseline: 1.0556x; 1.0222x over previous
.LBB0_278:
	v_ashrrev_i32_e32 v169, 31, v168
	s_lshl_b32 s6, s22, 8
	v_lshlrev_b64 v[128:129], 10, v[168:169]
	s_ashr_i32 s7, s6, 31
	v_lshl_add_u64 v[128:129], s[10:11], 0, v[128:129]
	s_lshl_b64 s[6:7], s[6:7], 2
	v_lshl_add_u64 v[128:129], v[128:129], 0, s[6:7]
	s_lshl_b32 s42, s81, 2
	s_mov_b32 s43, s27
	v_lshl_add_u64 v[128:129], v[128:129], 0, s[42:43]
	v_lshlrev_b32_e32 v144, 2, v154
	v_lshl_add_u64 v[128:129], v[128:129], 0, v[144:145]
	global_store_dwordx4 v[128:129], v[124:127], off
	global_store_dwordx4 v[128:129], v[120:123], off offset:16
	s_nop 1
	v_or_b32_e32 v104, 16, v168
	v_ashrrev_i32_e32 v105, 31, v104
	v_lshlrev_b64 v[104:105], 10, v[104:105]
	v_lshl_add_u64 v[104:105], s[10:11], 0, v[104:105]
	v_lshl_add_u64 v[104:105], v[104:105], 0, s[6:7]
	v_lshl_add_u64 v[104:105], v[104:105], 0, s[42:43]
	v_lshl_add_u64 v[104:105], v[104:105], 0, v[144:145]
	global_store_dwordx4 v[104:105], v[116:119], off
	global_store_dwordx4 v[104:105], v[112:115], off offset:16
	s_nop 1
	v_or_b32_e32 v88, 32, v168
	v_ashrrev_i32_e32 v89, 31, v88
	v_lshlrev_b64 v[88:89], 10, v[88:89]
	v_lshl_add_u64 v[88:89], s[10:11], 0, v[88:89]
	v_lshl_add_u64 v[88:89], v[88:89], 0, s[6:7]
	v_lshl_add_u64 v[88:89], v[88:89], 0, s[42:43]
	v_lshl_add_u64 v[88:89], v[88:89], 0, v[144:145]
	global_store_dwordx4 v[88:89], v[100:103], off
	global_store_dwordx4 v[88:89], v[96:99], off offset:16
	s_nop 1
	v_or_b32_e32 v72, 48, v168
	v_ashrrev_i32_e32 v73, 31, v72
	v_lshlrev_b64 v[72:73], 10, v[72:73]
	v_lshl_add_u64 v[72:73], s[10:11], 0, v[72:73]
	v_lshl_add_u64 v[72:73], v[72:73], 0, s[6:7]
	v_lshl_add_u64 v[72:73], v[72:73], 0, s[42:43]
	v_lshl_add_u64 v[72:73], v[72:73], 0, v[144:145]
	global_store_dwordx4 v[72:73], v[84:87], off
	global_store_dwordx4 v[72:73], v[80:83], off offset:16
	s_mov_b64 s[6:7], 0x20000
	s_nop 0
	v_add_co_u32_e32 v66, vcc, s95, v128
	v_lshl_add_u64 v[64:65], v[128:129], 0, s[6:7]
	s_nop 0
	v_addc_co_u32_e32 v67, vcc, 0, v129, vcc
	global_store_dwordx4 v[66:67], v[60:63], off
	global_store_dwordx4 v[64:65], v[56:59], off offset:16
	s_mov_b64 s[6:7], 0x24000
	s_nop 0
	v_add_co_u32_e32 v42, vcc, s67, v128
	v_lshl_add_u64 v[40:41], v[128:129], 0, s[6:7]
	s_nop 0
	v_addc_co_u32_e32 v43, vcc, 0, v129, vcc
	global_store_dwordx4 v[42:43], v[52:55], off
	global_store_dwordx4 v[40:41], v[48:51], off offset:16
	s_mov_b64 s[6:7], 0x28000
	s_nop 0
	v_add_co_u32_e32 v26, vcc, 0x28000, v128
	v_lshl_add_u64 v[24:25], v[128:129], 0, s[6:7]
	s_nop 0
	v_addc_co_u32_e32 v27, vcc, 0, v129, vcc
	global_store_dwordx4 v[26:27], v[36:39], off
	global_store_dwordx4 v[24:25], v[32:35], off offset:16
	s_mov_b64 s[6:7], 0x2c000
	s_nop 0
	v_add_co_u32_e32 v10, vcc, 0x2c000, v128
	v_lshl_add_u64 v[8:9], v[128:129], 0, s[6:7]
	s_nop 0
	v_addc_co_u32_e32 v11, vcc, 0, v129, vcc
	global_store_dwordx4 v[10:11], v[20:23], off
	global_store_dwordx4 v[8:9], v[16:19], off offset:16
	s_and_b64 vcc, exec, s[4:5]
	s_mov_b64 s[4:5], -1
	s_cbranch_vccnz .LBB0_227
	s_branch .LBB0_363

.LBB0_692:
	s_or_b64 exec, exec, s[4:5]
	s_lshl_b32 s0, s52, 3
	s_add_i32 s17, s16, s0
	s_mov_b32 s8, s17
	s_cmpk_lg_i32 s33, 0x100
	s_cbranch_scc1 .Lp1_keep
	s_add_i32 s8, s17, 0xfffffb80
.Lp1_keep:
	s_cmp_gt_u32 s8, 0xff
	s_cbranch_scc1 .LBB0_697
	v_readlane_b32 s0, v253, 55
	s_nop 0
	v_mov_b32_e32 v0, s0
	v_readlane_b32 s0, v253, 56
	s_nop 1
	v_mov_b32_e32 v4, s0
	ds_read_b128 v[0:3], v0
	ds_read_b64 v[86:87], v4

.LBB0_697:
	s_mov_b32 s98, 0xc400
	s_cmpk_lg_i32 s33, 0x100
	s_cbranch_scc1 .Ltr_entry
	s_movk_i32 s98, 0x3100
	s_add_i32 s17, s17, 0xfffffa80
	s_movk_i32 s64, 0x280
	s_cmp_lt_i32 s17, 0
	s_cselect_b32 s17, s98, s17

.Ldef_check:
	s_cmpk_lg_i32 s33, 0x100
	s_cbranch_scc1 .LBB0_743
	s_cmp_lt_i32 s44, 2
	s_cbranch_scc1 .LBB0_743
	s_add_i32 s0, s44, -2
	s_mul_i32 s1, s0, 47
	s_lshr_b32 s1, s1, 9
	s_mul_i32 s4, s1, 11
	s_sub_i32 s0, s0, s4
	s_cmp_gt_i32 s1, 2
	s_cbranch_scc1 .LBB0_743
	v_readlane_b32 s5, v254, 63
	s_cmp_lt_i32 s5, 0x80
	s_cbranch_scc1 .LBB0_743
	s_cmp_eq_u32 s0, 0
	s_cbranch_scc1 .Ldef_go0
	s_cmp_eq_u32 s0, 8
	s_cbranch_scc0 .LBB0_743
	s_movk_i32 s4, 0x400
	s_branch .Ldef_go
